# P1 deferred w_ple_gate transpose loads de-serialised (the idle-workgroup block no longer overruns the last GEMM round)
# speedup vs baseline: 1.0443x; 1.0110x over previous
; #define LAS __attribute__((address_space(3)))
; __device__ __forceinline__ void p0_transpose_item(const float* W, int N, bf16_t* WT, int ldt, int col_off, const float* kscale, LAS float* scr, int item, int lane, int nscale_from = -1) {
;     const int nblk = N / 32, kb = item / nblk, nb = item % nblk, k0 = 64 * kb, n0 = 32 * nb;
; #pragma unroll 16
;     for (int i = 0; i < 32; ++i) { const int kk = 2 * i + (lane >> 5); const float s = (kscale ? kscale[k0 + kk] : 1.f) * ((nscale_from >= 0 && n0 >= nscale_from) ? -LOG2E : 1.f); scr[kk * 33 + (lane & 31)] = __builtin_nontemporal_load(W + (size_t)(k0 + kk) * N + n0 + (lane & 31)) * s; }
; __global__ void __launch_bounds__(NWAVES * 64, 2) fwd_megakernel(Args args) {
;     ...
;                     if (r < I_G) { p0_transpose_item(w_ple_gate, DM, WGP_t, LDHP, 0, g_ple, scr, r, lane); continue; } r -= I_G;
.LBB0_399:
	v_lshl_add_u64 v[92:93], s[12:13], 0, v[58:59]
	s_mov_b64 s[10:11], 0x20000
	global_load_dword v146, v[92:93], off
	global_load_dword v147, v[92:93], off offset:8
	global_load_dword v148, v[92:93], off offset:16
	global_load_dword v149, v[92:93], off offset:24
	global_load_dword v150, v[92:93], off offset:32
	global_load_dword v151, v[92:93], off offset:40
	global_load_dword v152, v[92:93], off offset:48
	global_load_dword v153, v[92:93], off offset:56
	global_load_dword v154, v[92:93], off offset:64
	global_load_dword v155, v[92:93], off offset:72
	global_load_dword v156, v[92:93], off offset:80
	global_load_dword v157, v[92:93], off offset:88
	global_load_dword v158, v[92:93], off offset:96
	global_load_dword v159, v[92:93], off offset:104
	global_load_dword v160, v[92:93], off offset:112
	global_load_dword v161, v[92:93], off offset:120
	global_load_dword v164, v[92:93], off offset:128
	global_load_dword v165, v[92:93], off offset:136
	global_load_dword v166, v[92:93], off offset:144
	global_load_dword v167, v[92:93], off offset:152
	global_load_dword v168, v[92:93], off offset:160
	global_load_dword v169, v[92:93], off offset:168
	global_load_dword v170, v[92:93], off offset:176
	global_load_dword v171, v[92:93], off offset:184
	global_load_dword v172, v[92:93], off offset:192
	global_load_dword v173, v[92:93], off offset:200
	global_load_dword v174, v[92:93], off offset:208
	global_load_dword v175, v[92:93], off offset:216
	global_load_dword v176, v[92:93], off offset:224
	global_load_dword v177, v[92:93], off offset:232
	global_load_dword v178, v[92:93], off offset:240
	global_load_dword v179, v[92:93], off offset:248
	global_load_dword v180, v[88:89], off nt
	global_load_dword v181, v[86:87], off nt
	global_load_dword v182, v[84:85], off nt
	global_load_dword v183, v[82:83], off nt
	global_load_dword v184, v[80:81], off nt
	global_load_dword v185, v[78:79], off nt
	global_load_dword v186, v[76:77], off nt
	global_load_dword v187, v[74:75], off nt
	global_load_dword v188, v[72:73], off nt
	global_load_dword v189, v[70:71], off nt
	global_load_dword v190, v[68:69], off nt
	global_load_dword v191, v[66:67], off nt
	global_load_dword v192, v[64:65], off nt
	global_load_dword v193, v[62:63], off nt
	global_load_dword v198, v[60:61], off nt
	global_load_dword v199, v[56:57], off nt
	v_lshl_add_u64 v[118:119], v[88:89], 0, s[10:11]
	global_load_dword v200, v[118:119], off nt
	v_lshl_add_u64 v[118:119], v[86:87], 0, s[10:11]
	global_load_dword v201, v[118:119], off nt
	v_lshl_add_u64 v[118:119], v[84:85], 0, s[10:11]
	global_load_dword v202, v[118:119], off nt
	v_lshl_add_u64 v[118:119], v[82:83], 0, s[10:11]
	global_load_dword v203, v[118:119], off nt
	v_lshl_add_u64 v[118:119], v[80:81], 0, s[10:11]
	global_load_dword v204, v[118:119], off nt
	v_lshl_add_u64 v[118:119], v[78:79], 0, s[10:11]
	global_load_dword v205, v[118:119], off nt
	v_lshl_add_u64 v[118:119], v[76:77], 0, s[10:11]
	global_load_dword v206, v[118:119], off nt
	v_lshl_add_u64 v[118:119], v[74:75], 0, s[10:11]
	global_load_dword v207, v[118:119], off nt
	v_lshl_add_u64 v[118:119], v[72:73], 0, s[10:11]
	global_load_dword v208, v[118:119], off nt
	v_lshl_add_u64 v[118:119], v[70:71], 0, s[10:11]
	global_load_dword v209, v[118:119], off nt
	v_lshl_add_u64 v[118:119], v[68:69], 0, s[10:11]
	global_load_dword v210, v[118:119], off nt
	v_lshl_add_u64 v[118:119], v[66:67], 0, s[10:11]
	global_load_dword v211, v[118:119], off nt
	v_lshl_add_u64 v[118:119], v[64:65], 0, s[10:11]
	global_load_dword v212, v[118:119], off nt
	v_lshl_add_u64 v[118:119], v[62:63], 0, s[10:11]
	global_load_dword v213, v[118:119], off nt
	v_lshl_add_u64 v[118:119], v[60:61], 0, s[10:11]
	global_load_dword v214, v[118:119], off nt
	v_lshl_add_u64 v[118:119], v[56:57], 0, s[10:11]
	global_load_dword v215, v[118:119], off nt
	s_waitcnt vmcnt(31)
	v_mul_f32_e32 v92, v146, v180
	ds_write_b32 v100, v92
	s_waitcnt vmcnt(30)
	v_mul_f32_e32 v92, v147, v181
	ds_write_b32 v100, v92 offset:264
	s_waitcnt vmcnt(29)
	v_mul_f32_e32 v92, v148, v182
	ds_write_b32 v100, v92 offset:528
	s_waitcnt vmcnt(28)
	v_mul_f32_e32 v92, v149, v183
	ds_write_b32 v100, v92 offset:792
	s_waitcnt vmcnt(27)
	v_mul_f32_e32 v92, v150, v184
	ds_write_b32 v100, v92 offset:1056
	s_waitcnt vmcnt(26)
	v_mul_f32_e32 v92, v151, v185
	ds_write_b32 v100, v92 offset:1320
	s_waitcnt vmcnt(25)
	v_mul_f32_e32 v92, v152, v186
	ds_write_b32 v100, v92 offset:1584
	s_waitcnt vmcnt(24)
	v_mul_f32_e32 v92, v153, v187
	ds_write_b32 v100, v92 offset:1848
	s_waitcnt vmcnt(23)
	v_mul_f32_e32 v92, v154, v188
	ds_write_b32 v100, v92 offset:2112
	s_waitcnt vmcnt(22)
	v_mul_f32_e32 v92, v155, v189
	ds_write_b32 v100, v92 offset:2376
	s_waitcnt vmcnt(21)
	v_mul_f32_e32 v92, v156, v190
	ds_write_b32 v100, v92 offset:2640
	s_waitcnt vmcnt(20)
	v_mul_f32_e32 v92, v157, v191
	ds_write_b32 v100, v92 offset:2904
	s_waitcnt vmcnt(19)
	v_mul_f32_e32 v92, v158, v192
	ds_write_b32 v100, v92 offset:3168
	s_waitcnt vmcnt(18)
	v_mul_f32_e32 v92, v159, v193
	ds_write_b32 v100, v92 offset:3432
	s_waitcnt vmcnt(17)
	v_mul_f32_e32 v92, v160, v198
	ds_write_b32 v100, v92 offset:3696
	s_waitcnt vmcnt(16)
	v_mul_f32_e32 v92, v161, v199
	ds_write_b32 v100, v92 offset:3960
	s_waitcnt vmcnt(15)
	v_mul_f32_e32 v92, v164, v200
	ds_write_b32 v100, v92 offset:4224
	s_waitcnt vmcnt(14)
	v_mul_f32_e32 v92, v165, v201
	ds_write_b32 v100, v92 offset:4488
	s_waitcnt vmcnt(13)
	v_mul_f32_e32 v92, v166, v202
	ds_write_b32 v100, v92 offset:4752
	s_waitcnt vmcnt(12)
	v_mul_f32_e32 v92, v167, v203
	ds_write_b32 v100, v92 offset:5016
	s_waitcnt vmcnt(11)
	v_mul_f32_e32 v92, v168, v204
	ds_write_b32 v100, v92 offset:5280
	s_waitcnt vmcnt(10)
	v_mul_f32_e32 v92, v169, v205
	ds_write_b32 v100, v92 offset:5544
	s_waitcnt vmcnt(9)
	v_mul_f32_e32 v92, v170, v206
	ds_write_b32 v100, v92 offset:5808
	s_waitcnt vmcnt(8)
	v_mul_f32_e32 v92, v171, v207
	ds_write_b32 v100, v92 offset:6072
	s_waitcnt vmcnt(7)
	v_mul_f32_e32 v92, v172, v208
	ds_write_b32 v100, v92 offset:6336
	s_waitcnt vmcnt(6)
	v_mul_f32_e32 v92, v173, v209
	ds_write_b32 v100, v92 offset:6600
	s_waitcnt vmcnt(5)
	v_mul_f32_e32 v92, v174, v210
	ds_write_b32 v100, v92 offset:6864
	s_waitcnt vmcnt(4)
	v_mul_f32_e32 v92, v175, v211
	ds_write_b32 v100, v92 offset:7128
	s_waitcnt vmcnt(3)
	v_mul_f32_e32 v92, v176, v212
	ds_write_b32 v100, v92 offset:7392
	s_waitcnt vmcnt(2)
	v_mul_f32_e32 v92, v177, v213
	ds_write_b32 v100, v92 offset:7656
	s_waitcnt vmcnt(1)
	v_mul_f32_e32 v92, v178, v214
	ds_write_b32 v100, v92 offset:7920
	s_waitcnt vmcnt(0)
	v_mul_f32_e32 v92, v179, v215
	ds_write_b32 v100, v92 offset:8184
